# EpiRes bf16 h stores widened via v_permlane16_swap + dwordx4, swaps issued with no LDS op or VGPR-returning load outstanding (full wait on 2nd residual batch)
# speedup vs baseline: 1.0180x; 1.0054x over previous
; DI unsigned cvt_pk(float lo, float hi) { unsigned r; asm("v_cvt_pk_bf16_f32 %0, %1, %2" : "=v"(r) : "v"(lo), "v"(hi)); return r; }
; #define EPI_FENCE asm volatile("" ::: "memory")
;   DI void operator()(LAS unsigned char* lds, f32x4 (&acc)[2][2][4][2], int pm, int pn, int wr, int wc, int fr, int fq) const {
;     ...
;       for (int m = 0; m < 4; ++m)
; #pragma unroll
;         for (int bj = 0; bj < 2; ++bj)
; #pragma unroll
;           for (int n = 0; n < 2; ++n) rv[m][bj][n] = *(const f32x4*)(resid + base0 + (size_t)(ai * HALF + m * 16) * DM + bj * HALF + n * 16);
;       EPI_FENCE;
; #pragma unroll
;       for (int m = 0; m < 4; ++m) {
;         const size_t off0 = base0 + (size_t)(ai * HALF + m * 16) * DM;
;         float* op = hout + off0; bf16_t* bp = hb + off0;
;         float q = 0.f;
; #pragma unroll
;         for (int bj = 0; bj < 2; ++bj)
; #pragma unroll
;           for (int n = 0; n < 2; ++n) {
;             const f32x4 o = rv[m][bj][n] + acc[ai][bj][m][n];
;             *(f32x4*)(op + bj * HALF + n * 16) = o;
;             q += o[0] * o[0] + o[1] * o[1] + o[2] * o[2] + o[3] * o[3];
;             u32x2 w; w.x = cvt_pk(o[0], o[1]); w.y = cvt_pk(o[2], o[3]);
;             *(u32x2*)(bp + bj * HALF + n * 16) = w;
;           }
;         q += __shfl_xor(q, 16); q += __shfl_xor(q, 32);
;         if (fq == 0) red[(ai * HALF + wr * 64 + m * 16 + fr) * 4 + wc] = q;
;       }
.LBB0_115:
	s_or_b64 exec, exec, s[18:19]
	v_add_co_u32_e32 v134, vcc, 0x80000, v178
	s_mov_b64 s[18:19], 0x80000
	s_nop 0
	v_addc_co_u32_e32 v135, vcc, 0, v179, vcc
	global_load_dwordx4 v[126:129], v[134:135], off
	global_load_dwordx4 v[130:133], v[134:135], off offset:64
	global_load_dwordx4 v[118:121], v[134:135], off offset:512
	global_load_dwordx4 v[114:117], v[134:135], off offset:576
	v_add_co_u32_e32 v66, vcc, 0x90000, v178
	v_lshl_add_u64 v[122:123], v[178:179], 0, s[18:19]
	s_waitcnt lgkmcnt(0)
	v_addc_co_u32_e32 v67, vcc, 0, v179, vcc
	global_load_dwordx4 v[110:113], v[66:67], off
	global_load_dwordx4 v[106:109], v[66:67], off offset:64
	global_load_dwordx4 v[102:105], v[66:67], off offset:512
	global_load_dwordx4 v[98:101], v[66:67], off offset:576
	v_add_co_u32_e32 v66, vcc, 0xa0000, v178
	s_mov_b64 s[18:19], 0x40000
	s_nop 0
	v_addc_co_u32_e32 v67, vcc, 0, v179, vcc
	global_load_dwordx4 v[94:97], v[66:67], off
	global_load_dwordx4 v[90:93], v[66:67], off offset:64
	global_load_dwordx4 v[86:89], v[66:67], off offset:512
	global_load_dwordx4 v[78:81], v[66:67], off offset:576
	v_add_co_u32_e32 v66, vcc, 0xb0000, v178
	v_lshl_add_u64 v[124:125], v[180:181], 0, s[18:19]
	s_nop 0
	v_addc_co_u32_e32 v67, vcc, 0, v179, vcc
	global_load_dwordx4 v[82:85], v[66:67], off
	global_load_dwordx4 v[74:77], v[66:67], off offset:64
	global_load_dwordx4 v[70:73], v[66:67], off offset:512
	s_nop 0
	global_load_dwordx4 v[66:69], v[66:67], off offset:576
	s_waitcnt vmcnt(0)
	v_pk_add_f32 v[62:63], v[62:63], v[126:127]
	s_nop 0
	v_mul_f32_e32 v126, v63, v63
	v_pk_add_f32 v[64:65], v[64:65], v[128:129]
	v_fmac_f32_e32 v126, v62, v62
	global_store_dwordx4 v[134:135], v[62:65], off
	v_fmac_f32_e32 v126, v64, v64
	v_fmac_f32_e32 v126, v65, v65
	v_cvt_pk_bf16_f32 v62, v62, v63
	v_cvt_pk_bf16_f32 v63, v64, v65
	v_add_co_u32_e32 v64, vcc, s62, v180
	s_waitcnt vmcnt(15)
	v_pk_add_f32 v[58:59], v[58:59], v[130:131]
	v_addc_co_u32_e32 v65, vcc, 0, v181, vcc
	v_mov_b32_e32 v232, v62
	v_mov_b32_e32 v233, v63
	v_pk_add_f32 v[60:61], v[60:61], v[132:133]
	v_mul_f32_e32 v62, v59, v59
	global_store_dwordx4 v[122:123], v[58:61], off offset:64
	v_fmac_f32_e32 v62, v58, v58
	s_waitcnt vmcnt(16)
	v_pk_add_f32 v[54:55], v[54:55], v[118:119]
	v_cvt_pk_bf16_f32 v58, v58, v59
	v_cvt_pk_bf16_f32 v59, v60, v61
	v_mov_b32_e32 v234, v58
	v_mov_b32_e32 v235, v59
	v_pk_add_f32 v[56:57], v[56:57], v[120:121]
	v_mul_f32_e32 v58, v55, v55
	global_store_dwordx4 v[122:123], v[54:57], off offset:512
	v_fmac_f32_e32 v58, v54, v54
	s_waitcnt vmcnt(17)
	v_pk_add_f32 v[50:51], v[50:51], v[114:115]
	v_cvt_pk_bf16_f32 v54, v54, v55
	v_fmac_f32_e32 v62, v60, v60
	v_cvt_pk_bf16_f32 v55, v56, v57
	v_mov_b32_e32 v236, v54
	v_mov_b32_e32 v237, v55
	v_mul_f32_e32 v54, v51, v51
	v_fmac_f32_e32 v62, v61, v61
	v_fmac_f32_e32 v58, v56, v56
	v_pk_add_f32 v[52:53], v[52:53], v[116:117]
	v_fmac_f32_e32 v54, v50, v50
	v_add_f32_e32 v62, v126, v62
	v_fmac_f32_e32 v58, v57, v57
	v_fmac_f32_e32 v54, v52, v52
	v_add_f32_e32 v58, v62, v58
	v_fmac_f32_e32 v54, v53, v53
	global_store_dwordx4 v[122:123], v[50:53], off offset:576
	v_add_f32_e32 v54, v58, v54
	s_nop 0
	v_cvt_pk_bf16_f32 v50, v50, v51
	v_cvt_pk_bf16_f32 v51, v52, v53
	v_mov_b32_e32 v238, v50
	v_mov_b32_e32 v239, v51
	v_lshl_add_u64 v[230:231], v[124:125], 0, v[228:229]
	s_waitcnt lgkmcnt(0)
	s_nop 1
	v_permlane16_swap_b32_e32 v232, v234
	v_permlane16_swap_b32_e32 v233, v235
	v_permlane16_swap_b32_e32 v236, v238
	v_permlane16_swap_b32_e32 v237, v239
	global_store_dwordx4 v[230:231], v[232:235], off
	global_store_dwordx4 v[230:231], v[236:239], off offset:256
	ds_bpermute_b32 v50, v182, v54
	s_waitcnt lgkmcnt(0)
	v_add_f32_e32 v50, v54, v50
	ds_bpermute_b32 v51, v146, v50
	s_and_saveexec_b64 s[18:19], s[42:43]
	s_cbranch_execz .LBB0_117
	s_waitcnt lgkmcnt(0)
	v_add_f32_e32 v50, v50, v51
	ds_write_b32 v0, v50 offset:2048

; DI unsigned cvt_pk(float lo, float hi) { unsigned r; asm("v_cvt_pk_bf16_f32 %0, %1, %2" : "=v"(r) : "v"(lo), "v"(hi)); return r; }
; #define EPI_FENCE asm volatile("" ::: "memory")
;   DI void operator()(LAS unsigned char* lds, f32x4 (&acc)[2][2][4][2], int pm, int pn, int wr, int wc, int fr, int fq) const {
;     ...
;       for (int m = 0; m < 4; ++m)
; #pragma unroll
;         for (int bj = 0; bj < 2; ++bj)
; #pragma unroll
;           for (int n = 0; n < 2; ++n) rv[m][bj][n] = *(const f32x4*)(resid + base0 + (size_t)(ai * HALF + m * 16) * DM + bj * HALF + n * 16);
;       EPI_FENCE;
; #pragma unroll
;       for (int m = 0; m < 4; ++m) {
;         const size_t off0 = base0 + (size_t)(ai * HALF + m * 16) * DM;
;         float* op = hout + off0; bf16_t* bp = hb + off0;
;         float q = 0.f;
; #pragma unroll
;         for (int bj = 0; bj < 2; ++bj)
; #pragma unroll
;           for (int n = 0; n < 2; ++n) {
;             const f32x4 o = rv[m][bj][n] + acc[ai][bj][m][n];
;             *(f32x4*)(op + bj * HALF + n * 16) = o;
;             q += o[0] * o[0] + o[1] * o[1] + o[2] * o[2] + o[3] * o[3];
;             u32x2 w; w.x = cvt_pk(o[0], o[1]); w.y = cvt_pk(o[2], o[3]);
;             *(u32x2*)(bp + bj * HALF + n * 16) = w;
;           }
;         q += __shfl_xor(q, 16); q += __shfl_xor(q, 32);
;         if (fq == 0) red[(ai * HALF + wr * 64 + m * 16 + fr) * 4 + wc] = q;
;       }
.LBB0_520:
	s_or_b64 exec, exec, s[18:19]
	v_add_co_u32_e32 v66, vcc, 0x80000, v182
	s_mov_b32 s15, 0x80000
	s_waitcnt lgkmcnt(0)
	v_addc_co_u32_e32 v67, vcc, 0, v183, vcc
	global_load_dwordx4 v[124:127], v[66:67], off
	global_load_dwordx4 v[128:131], v[66:67], off offset:64
	global_load_dwordx4 v[118:121], v[66:67], off offset:512
	global_load_dwordx4 v[114:117], v[66:67], off offset:576
	v_add_co_u32_e32 v66, vcc, 0x90000, v182
	s_mov_b64 s[16:17], 0x80000
	s_nop 0
	v_addc_co_u32_e32 v67, vcc, 0, v183, vcc
	global_load_dwordx4 v[110:113], v[66:67], off
	global_load_dwordx4 v[106:109], v[66:67], off offset:64
	global_load_dwordx4 v[102:105], v[66:67], off offset:512
	global_load_dwordx4 v[98:101], v[66:67], off offset:576
	v_add_co_u32_e32 v66, vcc, 0xa0000, v182
	v_lshl_add_u64 v[132:133], v[180:181], 0, s[16:17]
	s_nop 0
	v_addc_co_u32_e32 v67, vcc, 0, v183, vcc
	global_load_dwordx4 v[94:97], v[66:67], off
	global_load_dwordx4 v[90:93], v[66:67], off offset:64
	global_load_dwordx4 v[86:89], v[66:67], off offset:512
	global_load_dwordx4 v[78:81], v[66:67], off offset:576
	v_add_co_u32_e32 v66, vcc, 0xb0000, v182
	s_mov_b64 s[16:17], 0x40000
	s_nop 0
	v_addc_co_u32_e32 v67, vcc, 0, v183, vcc
	global_load_dwordx4 v[82:85], v[66:67], off
	global_load_dwordx4 v[74:77], v[66:67], off offset:64
	global_load_dwordx4 v[70:73], v[66:67], off offset:512
	s_nop 0
	global_load_dwordx4 v[66:69], v[66:67], off offset:576
	v_lshl_add_u64 v[122:123], v[178:179], 0, s[16:17]
	s_waitcnt vmcnt(0)
	v_pk_add_f32 v[62:63], v[62:63], v[124:125]
	v_add_co_u32_e32 v124, vcc, s15, v180
	v_pk_add_f32 v[64:65], v[64:65], v[126:127]
	s_nop 0
	v_addc_co_u32_e32 v125, vcc, 0, v181, vcc
	global_store_dwordx4 v[124:125], v[62:65], off
	v_mul_f32_e32 v124, v63, v63
	v_fmac_f32_e32 v124, v62, v62
	s_mov_b32 s15, 0x40000
	v_fmac_f32_e32 v124, v64, v64
	v_cvt_pk_bf16_f32 v62, v62, v63
	v_cvt_pk_bf16_f32 v63, v64, v65
	v_add_co_u32_e32 v64, vcc, s15, v178
	v_fmac_f32_e32 v124, v65, v65
	s_nop 0
	v_addc_co_u32_e32 v65, vcc, 0, v179, vcc
	s_waitcnt vmcnt(15)
	v_pk_add_f32 v[58:59], v[58:59], v[128:129]
	v_mov_b32_e32 v232, v62
	v_mov_b32_e32 v233, v63
	v_pk_add_f32 v[60:61], v[60:61], v[130:131]
	v_mul_f32_e32 v62, v59, v59
	global_store_dwordx4 v[132:133], v[58:61], off offset:64
	v_fmac_f32_e32 v62, v58, v58
	s_waitcnt vmcnt(16)
	v_pk_add_f32 v[54:55], v[54:55], v[118:119]
	v_cvt_pk_bf16_f32 v58, v58, v59
	v_cvt_pk_bf16_f32 v59, v60, v61
	v_mov_b32_e32 v234, v58
	v_mov_b32_e32 v235, v59
	v_pk_add_f32 v[56:57], v[56:57], v[120:121]
	v_mul_f32_e32 v58, v55, v55
	global_store_dwordx4 v[132:133], v[54:57], off offset:512
	v_fmac_f32_e32 v58, v54, v54
	s_waitcnt vmcnt(17)
	v_pk_add_f32 v[50:51], v[50:51], v[114:115]
	v_cvt_pk_bf16_f32 v54, v54, v55
	v_fmac_f32_e32 v62, v60, v60
	v_cvt_pk_bf16_f32 v55, v56, v57
	v_mov_b32_e32 v236, v54
	v_mov_b32_e32 v237, v55
	v_mul_f32_e32 v54, v51, v51
	v_fmac_f32_e32 v62, v61, v61
	v_fmac_f32_e32 v58, v56, v56
	v_pk_add_f32 v[52:53], v[52:53], v[116:117]
	v_fmac_f32_e32 v54, v50, v50
	v_add_f32_e32 v62, v124, v62
	v_fmac_f32_e32 v58, v57, v57
	v_fmac_f32_e32 v54, v52, v52
	v_add_f32_e32 v58, v62, v58
	v_fmac_f32_e32 v54, v53, v53
	global_store_dwordx4 v[132:133], v[50:53], off offset:576
	v_add_f32_e32 v54, v58, v54
	s_nop 0
	v_cvt_pk_bf16_f32 v50, v50, v51
	v_cvt_pk_bf16_f32 v51, v52, v53
	v_mov_b32_e32 v238, v50
	v_mov_b32_e32 v239, v51
	v_lshl_add_u64 v[230:231], v[122:123], 0, v[228:229]
	s_waitcnt lgkmcnt(0)
	s_nop 1
	v_permlane16_swap_b32_e32 v232, v234
	v_permlane16_swap_b32_e32 v233, v235
	v_permlane16_swap_b32_e32 v236, v238
	v_permlane16_swap_b32_e32 v237, v239
	global_store_dwordx4 v[230:231], v[232:235], off
	global_store_dwordx4 v[230:231], v[236:239], off offset:256
	ds_bpermute_b32 v50, v184, v54
	s_waitcnt lgkmcnt(0)
	v_add_f32_e32 v50, v54, v50
	ds_bpermute_b32 v51, v146, v50
	s_and_saveexec_b64 s[18:19], s[42:43]
	s_cbranch_execz .LBB0_522
	s_waitcnt lgkmcnt(0)
	v_add_f32_e32 v50, v50, v51
	ds_write_b32 v0, v50 offset:2048
